# s5_setup Kt loop rewritten: LDS reads double-buffered one iteration ahead, scalar mul/fma/add in the original rounding order
# speedup vs baseline: 1.0260x; 1.0094x over previous
.LBB0_660:
	s_or_b64 exec, exec, s[30:31]
	v_ashrrev_i32_e32 v0, 4, v20
	v_readlane_b32 s2, v255, 5
	v_mov_b32_e32 v2, 0
	v_lshl_add_u32 v22, v0, 3, 0
	v_lshl_add_u32 v21, v18, 9, s2
	s_add_i32 s2, 0, 0x4200
	s_mov_b32 s4, 0
	v_mov_b32_e32 v3, v2
	v_mov_b32_e32 v4, v2
	v_mov_b32_e32 v5, v2
	v_mov_b32_e32 v14, v2
	v_mov_b32_e32 v15, v2
	v_mov_b32_e32 v16, v2
	v_mov_b32_e32 v17, v2
	v_mov_b32_e32 v10, v2
	v_mov_b32_e32 v11, v2
	v_mov_b32_e32 v12, v2
	v_mov_b32_e32 v13, v2
	v_mov_b32_e32 v6, v2
	v_mov_b32_e32 v7, v2
	v_mov_b32_e32 v8, v2
	v_mov_b32_e32 v9, v2
	s_waitcnt lgkmcnt(0)
	s_barrier
	v_add_u32_e32 v23, s4, v21
	ds_read_b128 v[24:27], v23
	ds_read2_b64 v[28:31], v22 offset1:33
	v_mov_b32_e32 v23, s2
	ds_read_b128 v[32:35], v23
	ds_read_b128 v[36:39], v23 offset:16
	ds_read_b128 v[40:43], v23 offset:32
	ds_read_b128 v[44:47], v23 offset:48
	ds_read_b128 v[48:51], v23 offset:64
	ds_read_b128 v[52:55], v23 offset:80
	ds_read_b128 v[56:59], v23 offset:96
	ds_read_b128 v[60:63], v23 offset:112
	ds_read_b128 v[64:67], v23 offset:128
	ds_read_b128 v[68:71], v23 offset:144
	ds_read_b128 v[72:75], v23 offset:160
	ds_read_b128 v[76:79], v23 offset:176
	s_waitcnt lgkmcnt(14)
	ds_read_b128 v[80:83], v23 offset:192
	ds_read_b128 v[84:87], v23 offset:208
	ds_read_b128 v[88:91], v23 offset:224
	ds_read_b128 v[92:95], v23 offset:240
	s_add_i32 s4, s4, 16
	s_addk_i32 s2, 0x100
	v_add_u32_e32 v22, 0x210, v22
.Lkt_loop:
	v_add_u32_e32 v23, s4, v21
	ds_read_b128 v[96:99], v23
	ds_read2_b64 v[100:103], v22 offset1:33
	v_mov_b32_e32 v23, s2
	ds_read_b128 v[120:123], v23
	ds_read_b128 v[124:127], v23 offset:16
	ds_read_b128 v[128:131], v23 offset:32
	ds_read_b128 v[132:135], v23 offset:48
	ds_read_b128 v[136:139], v23 offset:64
	ds_read_b128 v[140:143], v23 offset:80
	ds_read_b128 v[144:147], v23 offset:96
	ds_read_b128 v[148:151], v23 offset:112
	ds_read_b128 v[180:183], v23 offset:128
	ds_read_b128 v[184:187], v23 offset:144
	ds_read_b128 v[188:191], v23 offset:160
	ds_read_b128 v[192:195], v23 offset:176
	s_waitcnt lgkmcnt(14)
	ds_read_b128 v[196:199], v23 offset:192
	ds_read_b128 v[200:203], v23 offset:208
	ds_read_b128 v[204:207], v23 offset:224
	ds_read_b128 v[208:211], v23 offset:240
	s_add_i32 s4, s4, 16
	s_addk_i32 s2, 0x100
	v_add_u32_e32 v22, 0x210, v22
	v_mul_f32_e32 v104, v24, v28
	v_mul_f32_e32 v105, v25, v29
	v_mul_f32_e32 v106, v25, v28
	v_mul_f32_e32 v107, v24, v29
	v_sub_f32_e32 v110, v104, v105
	v_add_f32_e32 v111, v106, v107
	v_mul_f32_e32 v104, v111, v33
	v_mul_f32_e32 v105, v111, v35
	v_mul_f32_e32 v106, v111, v37
	v_mul_f32_e32 v107, v111, v39
	v_fma_f32 v104, v32, v110, -v104
	v_fma_f32 v105, v34, v110, -v105
	v_fma_f32 v106, v36, v110, -v106
	v_fma_f32 v107, v38, v110, -v107
	v_add_f32_e32 v2, v2, v104
	v_add_f32_e32 v3, v3, v105
	v_add_f32_e32 v4, v4, v106
	v_add_f32_e32 v5, v5, v107
	v_mul_f32_e32 v104, v111, v41
	v_mul_f32_e32 v105, v111, v43
	v_mul_f32_e32 v106, v111, v45
	v_mul_f32_e32 v107, v111, v47
	v_fma_f32 v104, v40, v110, -v104
	v_fma_f32 v105, v42, v110, -v105
	v_fma_f32 v106, v44, v110, -v106
	v_fma_f32 v107, v46, v110, -v107
	v_add_f32_e32 v14, v14, v104
	v_add_f32_e32 v15, v15, v105
	v_add_f32_e32 v16, v16, v106
	v_add_f32_e32 v17, v17, v107
	v_mul_f32_e32 v104, v111, v49
	v_mul_f32_e32 v105, v111, v51
	v_mul_f32_e32 v106, v111, v53
	v_mul_f32_e32 v107, v111, v55
	v_fma_f32 v104, v48, v110, -v104
	v_fma_f32 v105, v50, v110, -v105
	v_fma_f32 v106, v52, v110, -v106
	v_fma_f32 v107, v54, v110, -v107
	v_add_f32_e32 v10, v10, v104
	v_add_f32_e32 v11, v11, v105
	v_add_f32_e32 v12, v12, v106
	v_add_f32_e32 v13, v13, v107
	v_mul_f32_e32 v104, v111, v57
	v_mul_f32_e32 v105, v111, v59
	v_mul_f32_e32 v106, v111, v61
	v_mul_f32_e32 v107, v111, v63
	v_fma_f32 v104, v56, v110, -v104
	v_fma_f32 v105, v58, v110, -v105
	v_fma_f32 v106, v60, v110, -v106
	v_fma_f32 v107, v62, v110, -v107
	v_add_f32_e32 v6, v6, v104
	v_add_f32_e32 v7, v7, v105
	v_add_f32_e32 v8, v8, v106
	v_add_f32_e32 v9, v9, v107
	v_mul_f32_e32 v104, v26, v30
	v_mul_f32_e32 v105, v27, v31
	v_mul_f32_e32 v106, v27, v30
	v_mul_f32_e32 v107, v26, v31
	v_sub_f32_e32 v110, v104, v105
	v_add_f32_e32 v111, v106, v107
	v_mul_f32_e32 v104, v111, v65
	v_mul_f32_e32 v105, v111, v67
	v_mul_f32_e32 v106, v111, v69
	v_mul_f32_e32 v107, v111, v71
	v_fma_f32 v104, v64, v110, -v104
	v_fma_f32 v105, v66, v110, -v105
	v_fma_f32 v106, v68, v110, -v106
	v_fma_f32 v107, v70, v110, -v107
	v_add_f32_e32 v2, v2, v104
	v_add_f32_e32 v3, v3, v105
	v_add_f32_e32 v4, v4, v106
	v_add_f32_e32 v5, v5, v107
	v_mul_f32_e32 v104, v111, v73
	v_mul_f32_e32 v105, v111, v75
	v_mul_f32_e32 v106, v111, v77
	v_mul_f32_e32 v107, v111, v79
	v_fma_f32 v104, v72, v110, -v104
	v_fma_f32 v105, v74, v110, -v105
	v_fma_f32 v106, v76, v110, -v106
	v_fma_f32 v107, v78, v110, -v107
	v_add_f32_e32 v14, v14, v104
	v_add_f32_e32 v15, v15, v105
	v_add_f32_e32 v16, v16, v106
	v_add_f32_e32 v17, v17, v107
	v_mul_f32_e32 v104, v111, v81
	v_mul_f32_e32 v105, v111, v83
	v_mul_f32_e32 v106, v111, v85
	v_mul_f32_e32 v107, v111, v87
	v_fma_f32 v104, v80, v110, -v104
	v_fma_f32 v105, v82, v110, -v105
	v_fma_f32 v106, v84, v110, -v106
	v_fma_f32 v107, v86, v110, -v107
	v_add_f32_e32 v10, v10, v104
	v_add_f32_e32 v11, v11, v105
	v_add_f32_e32 v12, v12, v106
	v_add_f32_e32 v13, v13, v107
	v_mul_f32_e32 v104, v111, v89
	v_mul_f32_e32 v105, v111, v91
	v_mul_f32_e32 v106, v111, v93
	v_mul_f32_e32 v107, v111, v95
	v_fma_f32 v104, v88, v110, -v104
	v_fma_f32 v105, v90, v110, -v105
	v_fma_f32 v106, v92, v110, -v106
	v_fma_f32 v107, v94, v110, -v107
	v_add_f32_e32 v6, v6, v104
	v_add_f32_e32 v7, v7, v105
	v_add_f32_e32 v8, v8, v106
	v_add_f32_e32 v9, v9, v107
	v_add_u32_e32 v23, s4, v21
	ds_read_b128 v[24:27], v23
	ds_read2_b64 v[28:31], v22 offset1:33
	v_mov_b32_e32 v23, s2
	ds_read_b128 v[32:35], v23
	ds_read_b128 v[36:39], v23 offset:16
	ds_read_b128 v[40:43], v23 offset:32
	ds_read_b128 v[44:47], v23 offset:48
	ds_read_b128 v[48:51], v23 offset:64
	ds_read_b128 v[52:55], v23 offset:80
	ds_read_b128 v[56:59], v23 offset:96
	ds_read_b128 v[60:63], v23 offset:112
	ds_read_b128 v[64:67], v23 offset:128
	ds_read_b128 v[68:71], v23 offset:144
	ds_read_b128 v[72:75], v23 offset:160
	ds_read_b128 v[76:79], v23 offset:176
	s_waitcnt lgkmcnt(14)
	ds_read_b128 v[80:83], v23 offset:192
	ds_read_b128 v[84:87], v23 offset:208
	ds_read_b128 v[88:91], v23 offset:224
	ds_read_b128 v[92:95], v23 offset:240
	s_add_i32 s4, s4, 16
	s_addk_i32 s2, 0x100
	v_add_u32_e32 v22, 0x210, v22
	v_mul_f32_e32 v104, v96, v100
	v_mul_f32_e32 v105, v97, v101
	v_mul_f32_e32 v106, v97, v100
	v_mul_f32_e32 v107, v96, v101
	v_sub_f32_e32 v110, v104, v105
	v_add_f32_e32 v111, v106, v107
	v_mul_f32_e32 v104, v111, v121
	v_mul_f32_e32 v105, v111, v123
	v_mul_f32_e32 v106, v111, v125
	v_mul_f32_e32 v107, v111, v127
	v_fma_f32 v104, v120, v110, -v104
	v_fma_f32 v105, v122, v110, -v105
	v_fma_f32 v106, v124, v110, -v106
	v_fma_f32 v107, v126, v110, -v107
	v_add_f32_e32 v2, v2, v104
	v_add_f32_e32 v3, v3, v105
	v_add_f32_e32 v4, v4, v106
	v_add_f32_e32 v5, v5, v107
	v_mul_f32_e32 v104, v111, v129
	v_mul_f32_e32 v105, v111, v131
	v_mul_f32_e32 v106, v111, v133
	v_mul_f32_e32 v107, v111, v135
	v_fma_f32 v104, v128, v110, -v104
	v_fma_f32 v105, v130, v110, -v105
	v_fma_f32 v106, v132, v110, -v106
	v_fma_f32 v107, v134, v110, -v107
	v_add_f32_e32 v14, v14, v104
	v_add_f32_e32 v15, v15, v105
	v_add_f32_e32 v16, v16, v106
	v_add_f32_e32 v17, v17, v107
	v_mul_f32_e32 v104, v111, v137
	v_mul_f32_e32 v105, v111, v139
	v_mul_f32_e32 v106, v111, v141
	v_mul_f32_e32 v107, v111, v143
	v_fma_f32 v104, v136, v110, -v104
	v_fma_f32 v105, v138, v110, -v105
	v_fma_f32 v106, v140, v110, -v106
	v_fma_f32 v107, v142, v110, -v107
	v_add_f32_e32 v10, v10, v104
	v_add_f32_e32 v11, v11, v105
	v_add_f32_e32 v12, v12, v106
	v_add_f32_e32 v13, v13, v107
	v_mul_f32_e32 v104, v111, v145
	v_mul_f32_e32 v105, v111, v147
	v_mul_f32_e32 v106, v111, v149
	v_mul_f32_e32 v107, v111, v151
	v_fma_f32 v104, v144, v110, -v104
	v_fma_f32 v105, v146, v110, -v105
	v_fma_f32 v106, v148, v110, -v106
	v_fma_f32 v107, v150, v110, -v107
	v_add_f32_e32 v6, v6, v104
	v_add_f32_e32 v7, v7, v105
	v_add_f32_e32 v8, v8, v106
	v_add_f32_e32 v9, v9, v107
	v_mul_f32_e32 v104, v98, v102
	v_mul_f32_e32 v105, v99, v103
	v_mul_f32_e32 v106, v99, v102
	v_mul_f32_e32 v107, v98, v103
	v_sub_f32_e32 v110, v104, v105
	v_add_f32_e32 v111, v106, v107
	v_mul_f32_e32 v104, v111, v181
	v_mul_f32_e32 v105, v111, v183
	v_mul_f32_e32 v106, v111, v185
	v_mul_f32_e32 v107, v111, v187
	v_fma_f32 v104, v180, v110, -v104
	v_fma_f32 v105, v182, v110, -v105
	v_fma_f32 v106, v184, v110, -v106
	v_fma_f32 v107, v186, v110, -v107
	v_add_f32_e32 v2, v2, v104
	v_add_f32_e32 v3, v3, v105
	v_add_f32_e32 v4, v4, v106
	v_add_f32_e32 v5, v5, v107
	v_mul_f32_e32 v104, v111, v189
	v_mul_f32_e32 v105, v111, v191
	v_mul_f32_e32 v106, v111, v193
	v_mul_f32_e32 v107, v111, v195
	v_fma_f32 v104, v188, v110, -v104
	v_fma_f32 v105, v190, v110, -v105
	v_fma_f32 v106, v192, v110, -v106
	v_fma_f32 v107, v194, v110, -v107
	v_add_f32_e32 v14, v14, v104
	v_add_f32_e32 v15, v15, v105
	v_add_f32_e32 v16, v16, v106
	v_add_f32_e32 v17, v17, v107
	v_mul_f32_e32 v104, v111, v197
	v_mul_f32_e32 v105, v111, v199
	v_mul_f32_e32 v106, v111, v201
	v_mul_f32_e32 v107, v111, v203
	v_fma_f32 v104, v196, v110, -v104
	v_fma_f32 v105, v198, v110, -v105
	v_fma_f32 v106, v200, v110, -v106
	v_fma_f32 v107, v202, v110, -v107
	v_add_f32_e32 v10, v10, v104
	v_add_f32_e32 v11, v11, v105
	v_add_f32_e32 v12, v12, v106
	v_add_f32_e32 v13, v13, v107
	v_mul_f32_e32 v104, v111, v205
	v_mul_f32_e32 v105, v111, v207
	v_mul_f32_e32 v106, v111, v209
	v_mul_f32_e32 v107, v111, v211
	v_fma_f32 v104, v204, v110, -v104
	v_fma_f32 v105, v206, v110, -v105
	v_fma_f32 v106, v208, v110, -v106
	v_fma_f32 v107, v210, v110, -v107
	v_add_f32_e32 v6, v6, v104
	v_add_f32_e32 v7, v7, v105
	v_add_f32_e32 v8, v8, v106
	v_add_f32_e32 v9, v9, v107
	s_cmpk_lg_i32 s4, 0x210
	s_cbranch_scc1 .Lkt_loop
	s_waitcnt lgkmcnt(0)
	v_mul_lo_u32 v0, v0, s37
	v_lshlrev_b32_e32 v18, 6, v18
	s_lshl_b32 s2, s36, 9
	v_add3_u32 v0, 0, v0, v18
	s_and_b32 s2, s2, 0x200
	ds_write_b128 v0, v[2:5] offset:33280
	ds_write_b128 v0, v[14:17] offset:33296
	ds_write_b128 v0, v[10:13] offset:33312
	ds_write_b128 v0, v[6:9] offset:33328
	v_add_u32_e32 v2, s2, v20
	s_movk_i32 s2, 0x4000
	v_cmp_gt_i32_e32 vcc, s2, v2
	s_waitcnt lgkmcnt(0)
	s_barrier
	s_and_saveexec_b64 s[4:5], vcc
	s_cbranch_execz .LBB0_667
	s_mov_b32 s11, s51
	s_lshl_b64 s[2:3], s[10:11], 18
	s_add_u32 s2, s12, s2
	v_and_b32_e32 v0, 63, v19
	s_addc_u32 s3, s13, s3
	v_lshlrev_b32_e32 v0, 4, v0
	v_bfe_u32 v3, v19, 1, 5
	v_lshl_add_u64 v[4:5], s[2:3], 0, v[0:1]
	s_mov_b64 s[2:3], 0xa500000
	v_xor_b32_e32 v3, 31, v3
	v_lshl_add_u64 v[4:5], v[4:5], 0, s[2:3]
	v_lshlrev_b32_e32 v0, 6, v2
	s_mov_b64 s[6:7], 0
	v_mov_b32_e32 v8, v2
	s_branch .LBB0_665
